# v12
# speedup vs baseline: 1.0024x; 1.0024x over previous
; #define LAS __attribute__((address_space(3)))
; __device__ __forceinline__ void convert_matrix(const Ctx& C, const float* W, int K, int N, bf16* WT, int mode, const float* gs) {
;     LAS float* scr = (LAS float*)(C.lds + C.wave * 16384);
;     const int gw = C.bid * 8 + C.wave, NGW = C.G * 8;
;     const int nblk = N / 32, nitems = (K / 64) * nblk;
;     for (int it = gw; it < nitems; it += NGW) {
;         const int kb = it / nblk, nb = it % nblk, n0 = nb * 32;
;         int drow0 = n0;
;         if (mode == 1) { const int j = n0 < DFF ? n0 : n0 - DFF; drow0 = 256 * (j >> 7) + (j & 127) + (n0 < DFF ? 0 : 128); }
;         transpose_item(W, K, N, WT, kb * 64, n0, drow0, scr, C.lane, gs, mode);
;     }
; }
; __device__ __forceinline__ void convert_layer(const Ctx& C, int li) {
;     unsigned char* wl = C.ws + WS_W + (size_t)li * WL_SIZE;
;     convert_matrix(C, C.in[3] + (size_t)li * D * NPROJ, D, NPROJ, (bf16*)(wl + WL_IN), 2, C.in[2] + (size_t)li * D);
;     convert_matrix(C, C.in[13] + (size_t)li * D * D, D, D, (bf16*)(wl + WL_OUT), 0, nullptr);
;     convert_matrix(C, C.in[15] + (size_t)li * D * 2 * DFF, D, 2 * DFF, (bf16*)(wl + WL_UP), 1, C.in[14] + (size_t)li * D);
;     convert_matrix(C, C.in[18] + (size_t)li * DFF * D, DFF, D, (bf16*)(wl + WL_DOWN), 0, nullptr);
;     convert_matrix(C, C.in[20] + (size_t)li * D * D, D, D, (bf16*)(wl + WL_GATE), 0, C.in[19] + (size_t)li * D);
;     convert_matrix(C, C.in[21] + (size_t)li * PLE * D, PLE, D, (bf16*)(wl + WL_PROJ), 0, nullptr);
.Lp0_loop:
	s_add_u32 s59, s58, s44
	s_cmp_lt_u32 s59, 43584
	s_cbranch_scc0 .Lp0_nonext
	s_mov_b32 s6, s59
	s_mov_b32 s7, 0
	s_cmp_lt_u32 s59, 26912
	s_cbranch_scc1 .Lp0_lay0_b
	s_sub_u32 s6, s59, 26912
	s_mov_b32 s7, 1

; __device__ __forceinline__ f32x4 mma16(bf16x8 x2, bf16x8 x1, f32x4 acc) { return __builtin_amdgcn_mfma_f32_16x16x32_bf16(x2, x1, acc, 0, 0, 0); }
; __device__ __forceinline__ void skinny_proj(const Ctx& C, const bf16* X, const bf16* Wt, const float* SS, bf16* PROJ) {
;     ...
;     for (int ks = 0; ks < D / 32; ++ks) {
;         const bf16x8 a = *(const bf16x8*)(A + ks * 32), b0 = *(const bf16x8*)(W0 + ks * 32), b1 = *(const bf16x8*)(W0 + (size_t)16 * D + ks * 32);
;         acc0 = mma16(b0, a, acc0); acc1 = mma16(b1, a, acc1);
;     }
.LBB0_323:
	v_lshl_add_u64 v[26:27], v[8:9], 0, s[6:7]
	v_add_co_u32_e32 v46, vcc, 0x1600000, v26
	v_lshl_add_u64 v[42:43], v[10:11], 0, s[6:7]
	s_nop 0
	v_addc_co_u32_e32 v47, vcc, 0, v27, vcc
	global_load_dwordx4 v[14:17], v[42:43], off offset:-256
	global_load_dwordx4 v[18:21], v[42:43], off offset:-192
	global_load_dwordx4 v[22:25], v[46:47], off
	v_add_co_u32_e32 v48, vcc, 0x1610000, v26
	s_add_u32 s6, s6, 0x200
	s_nop 0
	v_addc_co_u32_e32 v49, vcc, 0, v27, vcc
	global_load_dwordx4 v[26:29], v[46:47], off offset:64
	global_load_dwordx4 v[30:33], v[48:49], off
	s_addc_u32 s7, s7, 0
	s_cmpk_lg_i32 s6, 0x1000
	s_waitcnt vmcnt(0)
	v_mfma_f32_16x16x32_bf16 v[4:7], v[30:33], v[14:17], v[4:7]
	v_mfma_f32_16x16x32_bf16 v[0:3], v[22:25], v[14:17], v[0:3]
	global_load_dwordx4 v[22:25], v[48:49], off offset:64
	global_load_dwordx4 v[14:17], v[42:43], off offset:-128
	global_load_dwordx4 v[30:33], v[42:43], off offset:-64
	global_load_dwordx4 v[34:37], v[42:43], off
	v_mfma_f32_16x16x32_bf16 v[0:3], v[26:29], v[18:21], v[0:3]
	global_load_dwordx4 v[26:29], v[46:47], off offset:128
	global_load_dwordx4 v[38:41], v[46:47], off offset:192
	s_waitcnt vmcnt(1)
	v_mfma_f32_16x16x32_bf16 v[0:3], v[26:29], v[14:17], v[0:3]
	v_mfma_f32_16x16x32_bf16 v[4:7], v[22:25], v[18:21], v[4:7]
	global_load_dwordx4 v[18:21], v[48:49], off offset:128
	global_load_dwordx4 v[22:25], v[48:49], off offset:192
	s_waitcnt vmcnt(2)
	v_mfma_f32_16x16x32_bf16 v[0:3], v[38:41], v[30:33], v[0:3]
	s_waitcnt vmcnt(1)
	v_mfma_f32_16x16x32_bf16 v[4:7], v[18:21], v[14:17], v[4:7]
	global_load_dwordx4 v[14:17], v[42:43], off offset:64
	global_load_dwordx4 v[18:21], v[42:43], off offset:128
	global_load_dwordx4 v[26:29], v[42:43], off offset:192
	global_load_dwordx4 v[38:41], v[46:47], off offset:256
	s_nop 0
	global_load_dwordx4 v[42:45], v[46:47], off offset:320
	s_waitcnt vmcnt(5)
	v_mfma_f32_16x16x32_bf16 v[4:7], v[22:25], v[30:33], v[4:7]
	global_load_dwordx4 v[22:25], v[48:49], off offset:256
	global_load_dwordx4 v[30:33], v[48:49], off offset:320
	s_waitcnt vmcnt(3)
	v_mfma_f32_16x16x32_bf16 v[0:3], v[38:41], v[34:37], v[0:3]
	s_waitcnt vmcnt(1)
	v_mfma_f32_16x16x32_bf16 v[4:7], v[22:25], v[34:37], v[4:7]
	global_load_dwordx4 v[22:25], v[46:47], off offset:384
	global_load_dwordx4 v[34:37], v[48:49], off offset:384
	v_mfma_f32_16x16x32_bf16 v[0:3], v[42:45], v[14:17], v[0:3]
	s_waitcnt vmcnt(2)
	v_mfma_f32_16x16x32_bf16 v[4:7], v[30:33], v[14:17], v[4:7]
	global_load_dwordx4 v[14:17], v[46:47], off offset:448
	s_waitcnt vmcnt(2)
	v_mfma_f32_16x16x32_bf16 v[0:3], v[22:25], v[18:21], v[0:3]
	global_load_dwordx4 v[22:25], v[48:49], off offset:448
	s_waitcnt vmcnt(2)
	v_mfma_f32_16x16x32_bf16 v[4:7], v[34:37], v[18:21], v[4:7]
	s_waitcnt vmcnt(1)
	v_mfma_f32_16x16x32_bf16 v[0:3], v[14:17], v[26:29], v[0:3]
	s_waitcnt vmcnt(0)
	v_mfma_f32_16x16x32_bf16 v[4:7], v[22:25], v[26:29], v[4:7]
	s_cbranch_scc1 .LBB0_323
; #define LAS __attribute__((address_space(3)))
; __device__ __forceinline__ unsigned pk2(float lo, float hi) { return pg8::cvt_pk_bf16(lo, hi); }
; __device__ __forceinline__ void convert_matrix(const Ctx& C, const float* W, int K, int N, bf16* WT, int mode, const float* gs) {
;     LAS float* scr = (LAS float*)(C.lds + C.wave * 16384);
;     const int gw = C.bid * 8 + C.wave, NGW = C.G * 8;
;     const int nblk = N / 32, nitems = (K / 64) * nblk;
;     for (int it = gw; it < nitems; it += NGW) {
;         const int kb = it / nblk, nb = it % nblk, n0 = nb * 32;
;         int drow0 = n0;
;         if (mode == 1) { const int j = n0 < DFF ? n0 : n0 - DFF; drow0 = 256 * (j >> 7) + (j & 127) + (n0 < DFF ? 0 : 128); }
;         transpose_item(W, K, N, WT, kb * 64, n0, drow0, scr, C.lane, gs, mode);
; __device__ __forceinline__ void skinny_proj(const Ctx& C, const bf16* X, const bf16* Wt, const float* SS, bf16* PROJ) {
;     ...
;     const f32x4* p = (const f32x4*)(SS + (size_t)(r0 + fr) * 32); f32x4 sa = p[0];
; #pragma unroll
;     for (int q = 1; q < 8; ++q) sa = sa + p[q];
;     const float rs = rsqrtf(((sa[0] + sa[1]) + (sa[2] + sa[3])) * (1.0f / D) + EPS);
;     bf16* o = PROJ + (size_t)(r0 + fr) * LDP + NMAIN + 4 * fq;
;     *(v2u*)o = (v2u){pk2(acc0[0] * rs, acc0[1] * rs), pk2(acc0[2] * rs, acc0[3] * rs)};
;     *(v2u*)(o + 16) = (v2u){pk2(acc1[0] * rs, acc1[1] * rs), pk2(acc1[2] * rs, acc1[3] * rs)};
	s_addk_i32 s10, 0xc000
	v_or_b32_e32 v8, s10, v13
	v_add_u32_e32 v42, s11, v8
	v_ashrrev_i32_e32 v43, 31, v42
	v_lshlrev_b64 v[8:9], 7, v[42:43]
	v_lshl_add_u64 v[44:45], v[130:131], 0, v[8:9]
	global_load_dwordx4 v[8:11], v[44:45], off
	global_load_dwordx4 v[14:17], v[44:45], off offset:16
	global_load_dwordx4 v[18:21], v[44:45], off offset:32
	global_load_dwordx4 v[22:25], v[44:45], off offset:48
	global_load_dwordx4 v[26:29], v[44:45], off offset:64
	global_load_dwordx4 v[30:33], v[44:45], off offset:80
	global_load_dwordx4 v[34:37], v[44:45], off offset:96
	global_load_dwordx4 v[38:41], v[44:45], off offset:112
	v_and_b32_e32 v12, 3, v12
	s_movk_i32 s8, 0x2e00
	v_mov_b32_e32 v44, 0x358637bd
	v_mov_b32_e32 v13, 0
	v_lshlrev_b32_e32 v12, 3, v12
	v_mad_i64_i32 v[42:43], s[8:9], v42, s8, v[134:135]
	s_mov_b32 s10, 0x800000
	s_mov_b64 s[6:7], 0x2c00
	v_lshl_add_u64 v[12:13], v[42:43], 0, v[12:13]
	v_lshl_add_u64 v[42:43], v[12:13], 0, s[6:7]
	s_movk_i32 s11, 0x2000
	v_add_co_u32_e32 v12, vcc, s11, v12
	s_waitcnt vmcnt(6)
	v_pk_add_f32 v[10:11], v[10:11], v[16:17]
	v_pk_add_f32 v[8:9], v[8:9], v[14:15]
	s_waitcnt vmcnt(5)
	v_pk_add_f32 v[10:11], v[10:11], v[20:21]
	v_pk_add_f32 v[8:9], v[8:9], v[18:19]
	s_waitcnt vmcnt(4)
	v_pk_add_f32 v[10:11], v[10:11], v[24:25]
	v_pk_add_f32 v[8:9], v[8:9], v[22:23]
	s_waitcnt vmcnt(3)
	v_pk_add_f32 v[10:11], v[10:11], v[28:29]
	v_pk_add_f32 v[8:9], v[8:9], v[26:27]
	s_waitcnt vmcnt(2)
	v_pk_add_f32 v[10:11], v[10:11], v[32:33]
	v_pk_add_f32 v[8:9], v[8:9], v[30:31]
	s_waitcnt vmcnt(1)
	v_pk_add_f32 v[10:11], v[10:11], v[36:37]
	v_pk_add_f32 v[8:9], v[8:9], v[34:35]
	s_waitcnt vmcnt(0)
	v_pk_add_f32 v[10:11], v[10:11], v[40:41]
	v_pk_add_f32 v[8:9], v[8:9], v[38:39]
	v_addc_co_u32_e32 v13, vcc, 0, v13, vcc
	v_pk_mov_b32 v[14:15], v[8:9], v[10:11] op_sel:[1,0]
	v_mov_b32_e32 v9, v11
	v_pk_add_f32 v[8:9], v[14:15], v[8:9]
	s_nop 0
	v_add_f32_e32 v8, v8, v9
	v_fmac_f32_e32 v44, 0x3a000000, v8
	v_mul_f32_e32 v8, 0x4b800000, v44
	v_cmp_gt_f32_e64 s[6:7], s10, v44
	s_nop 1
	v_cndmask_b32_e64 v8, v44, v8, s[6:7]
	v_rsq_f32_e32 v8, v8
	s_nop 0
	v_mul_f32_e32 v9, 0x45800000, v8
	v_cndmask_b32_e64 v8, v8, v9, s[6:7]
	v_pk_mul_f32 v[0:1], v[0:1], v[8:9] op_sel_hi:[1,0]
	v_pk_mul_f32 v[2:3], v[2:3], v[8:9] op_sel_hi:[1,0]
	v_pk_mul_f32 v[4:5], v[4:5], v[8:9] op_sel_hi:[1,0]
	v_pk_mul_f32 v[6:7], v[6:7], v[8:9] op_sel_hi:[1,0]
	v_cvt_pk_bf16_f32 v0, v0, v1
	v_cvt_pk_bf16_f32 v1, v2, v3
	v_cvt_pk_bf16_f32 v2, v4, v5
	v_cvt_pk_bf16_f32 v3, v6, v7
	global_store_dwordx2 v[12:13], v[0:1], off offset:3072
	global_store_dwordx2 v[42:43], v[2:3], off offset:32
	v_writelane_b32 v250, s6, 0
	v_writelane_b32 v250, s7, 1
	v_writelane_b32 v250, s8, 2
	v_writelane_b32 v250, s9, 3
	v_writelane_b32 v250, s10, 4
	v_writelane_b32 v250, s11, 5
	v_writelane_b32 v250, s12, 6
	v_writelane_b32 v250, s13, 7
	v_writelane_b32 v250, s14, 8
	v_writelane_b32 v250, s15, 9
	v_writelane_b32 v250, s16, 10
	v_writelane_b32 v250, s17, 11
	v_writelane_b32 v250, s18, 12
	v_writelane_b32 v250, s19, 13
	v_writelane_b32 v250, s20, 14
	v_writelane_b32 v250, s21, 15
	v_writelane_b32 v250, s22, 16
	v_writelane_b32 v250, s23, 17
	v_writelane_b32 v250, s24, 18
	v_writelane_b32 v250, s25, 19
	v_writelane_b32 v250, s26, 20
	v_writelane_b32 v250, s27, 21
	v_writelane_b32 v250, s28, 22
	v_writelane_b32 v250, s29, 23
	v_writelane_b32 v250, s30, 24
	v_writelane_b32 v250, s31, 25
	v_writelane_b32 v250, s32, 26
	v_writelane_b32 v250, s33, 27
	v_writelane_b32 v250, s34, 28
	v_writelane_b32 v250, s35, 29
	v_writelane_b32 v250, s36, 30
	v_writelane_b32 v250, s37, 31
	v_writelane_b32 v250, s38, 32
	v_writelane_b32 v250, s39, 33
	v_writelane_b32 v250, s40, 34
	v_writelane_b32 v250, s41, 35
	v_writelane_b32 v250, s42, 36
	v_writelane_b32 v250, s43, 37
	v_writelane_b32 v250, s44, 38
	v_writelane_b32 v250, s45, 39
	v_writelane_b32 v250, s46, 40
	v_writelane_b32 v250, s47, 41
	v_writelane_b32 v250, s48, 42
	v_writelane_b32 v250, s49, 43
	v_writelane_b32 v250, s50, 44
	v_writelane_b32 v250, s51, 45
	v_writelane_b32 v250, s52, 46
	v_writelane_b32 v250, s53, 47
	v_writelane_b32 v250, s54, 48
	v_writelane_b32 v250, s55, 49
	v_writelane_b32 v250, s56, 50
	v_writelane_b32 v250, s57, 51
	v_writelane_b32 v250, s58, 52
	v_writelane_b32 v250, s59, 53
	v_writelane_b32 v250, s60, 54
	v_writelane_b32 v250, s61, 55
	v_writelane_b32 v250, s62, 56
	v_writelane_b32 v250, s63, 57
	v_writelane_b32 v250, s64, 58
	v_writelane_b32 v250, s65, 59
	v_writelane_b32 v250, s66, 60
	v_writelane_b32 v250, s67, 61
	v_writelane_b32 v250, s68, 62
	v_writelane_b32 v250, s69, 63
	v_writelane_b32 v251, s70, 0
	v_writelane_b32 v251, s71, 1
	v_writelane_b32 v251, s72, 2
	v_writelane_b32 v251, s73, 3
	v_writelane_b32 v251, s74, 4
	v_writelane_b32 v251, s75, 5
	v_writelane_b32 v251, s76, 6
	v_writelane_b32 v251, s77, 7
	v_writelane_b32 v251, s78, 8
	v_writelane_b32 v251, s79, 9
	s_load_dwordx4 s[24:27], s[0:1], 0x10
	s_load_dwordx2 s[28:29], s[0:1], 0x68
	s_load_dwordx4 s[36:39], s[0:1], 0x70
	s_load_dwordx2 s[30:31], s[0:1], 0x90
	s_load_dwordx4 s[40:43], s[0:1], 0x98
	s_load_dwordx2 s[34:35], s[0:1], 0xa8
	s_load_dwordx2 s[48:49], s[0:1], 0xc0
	s_load_dwordx4 s[64:67], s[0:1], 0x0
	v_readfirstlane_b32 s78, v234
	s_lshr_b32 s78, s78, 6
	s_sub_u32 s58, s2, 128
	s_lshl_b32 s58, s58, 3
	s_add_u32 s58, s58, s78
	s_add_u32 s58, s58, 43584
	s_lshl_b32 s78, s78, 14
	v_and_b32_e32 v1, 63, v234
	v_lshrrev_b32_e32 v6, 5, v1
	v_and_b32_e32 v7, 31, v1
	v_lshlrev_b32_e32 v7, 2, v7
	v_mul_u32_u24_e32 v2, 0x84, v6
	v_add3_u32 v2, s78, v2, v7
	v_and_b32_e32 v4, 7, v1
	v_lshrrev_b32_e32 v8, 3, v1
	v_mul_u32_u24_e32 v3, 0x420, v4
	v_lshlrev_b32_e32 v108, 2, v8
	v_add3_u32 v3, s78, v3, v108
	v_lshlrev_b32_e32 v5, 5, v4
	v_lshlrev_b32_e32 v4, 4, v4
	v_mov_b32_e32 v10, 0
	s_waitcnt lgkmcnt(0)
	s_mov_b32 s6, s58
	s_mov_b32 s7, 0
	s_cmp_lt_u32 s58, 26912
	s_cbranch_scc1 .Lq0_lay0_a
	s_sub_u32 s6, s58, 26912
	s_mov_b32 s7, 1

; __device__ __forceinline__ void convert_matrix(const Ctx& C, const float* W, int K, int N, bf16* WT, int mode, const float* gs) {
;     ...
;     for (int it = gw; it < nitems; it += NGW) {
;         const int kb = it / nblk, nb = it % nblk, n0 = nb * 32;
;         int drow0 = n0;
;         if (mode == 1) { const int j = n0 < DFF ? n0 : n0 - DFF; drow0 = 256 * (j >> 7) + (j & 127) + (n0 < DFF ? 0 : 128); }
;         transpose_item(W, K, N, WT, kb * 64, n0, drow0, scr, C.lane, gs, mode);
.Lq0_loop:
	s_add_u32 s59, s58, 1024
	s_cmp_lt_u32 s59, 53824
	s_cbranch_scc0 .Lq0_nonext
	s_mov_b32 s6, s59
	s_mov_b32 s7, 0
	s_cmp_lt_u32 s59, 26912
	s_cbranch_scc1 .Lq0_lay0_b
	s_sub_u32 s6, s59, 26912
	s_mov_b32 s7, 1

; #define LAS __attribute__((address_space(3)))
; __device__ __forceinline__ unsigned pk2(float lo, float hi) { return pg8::cvt_pk_bf16(lo, hi); }
; #define LDS_WAIT() asm volatile("s_waitcnt lgkmcnt(0)" ::: "memory")
; #pragma unroll 8
;     for (int i = 0; i < 32; ++i) { const int kk = 2 * i + (lane >> 5); const float sc = gs ? gs[k0 + kk] : 1.0f; scr[kk * 33 + (lane & 31)] = __builtin_nontemporal_load(W + (size_t)(k0 + kk) * N + n0 + (lane & 31)) * sc; }
;     LDS_WAIT();
;     const int c = lane & 7;
; #pragma unroll
;     for (int j = 0; j < 4; ++j) { const int n = (lane >> 3) + 8 * j; const LAS float* s = scr + (8 * c) * 33 + n;
;         v4u o; o.x = pk2(s[0 * 33], s[1 * 33]); o.y = pk2(s[2 * 33], s[3 * 33]); o.z = pk2(s[4 * 33], s[5 * 33]); o.w = pk2(s[6 * 33], s[7 * 33]);
;         const int drow = mode == 2 ? inproj_col(n0 + n) : drow0 + n;
;         *(v4u*)(WT + (size_t)drow * K + k0 + 8 * c) = o; }
;     LDS_WAIT();
; }
; __device__ __forceinline__ void convert_matrix(const Ctx& C, const float* W, int K, int N, bf16* WT, int mode, const float* gs) {
;     LAS float* scr = (LAS float*)(C.lds + C.wave * 16384);
;     const int gw = C.bid * 8 + C.wave, NGW = C.G * 8;
;     const int nblk = N / 32, nitems = (K / 64) * nblk;
;     for (int it = gw; it < nitems; it += NGW) {
;         const int kb = it / nblk, nb = it % nblk, n0 = nb * 32;
;         int drow0 = n0;
;         if (mode == 1) { const int j = n0 < DFF ? n0 : n0 - DFF; drow0 = 256 * (j >> 7) + (j & 127) + (n0 < DFF ? 0 : 128); }
;         transpose_item(W, K, N, WT, kb * 64, n0, drow0, scr, C.lane, gs, mode);
;     }
.Lq0_havegs:
	s_waitcnt lgkmcnt(12)
	v_pk_mul_f32 v[52:53], v[52:53], v[12:13]
	v_pk_mul_f32 v[54:55], v[54:55], v[14:15]
	v_pk_mul_f32 v[56:57], v[56:57], v[16:17]
	v_pk_mul_f32 v[58:59], v[58:59], v[18:19]
	v_cvt_pk_bf16_f32 v84, v52, v53
	v_cvt_pk_bf16_f32 v85, v54, v55
	v_cvt_pk_bf16_f32 v86, v56, v57
	v_cvt_pk_bf16_f32 v87, v58, v59
	global_store_dwordx4 v100, v[84:87], s[50:51]
	s_waitcnt lgkmcnt(8)
	v_pk_mul_f32 v[60:61], v[60:61], v[12:13]
	v_pk_mul_f32 v[62:63], v[62:63], v[14:15]
	v_pk_mul_f32 v[64:65], v[64:65], v[16:17]
	v_pk_mul_f32 v[66:67], v[66:67], v[18:19]
	v_cvt_pk_bf16_f32 v88, v60, v61
	v_cvt_pk_bf16_f32 v89, v62, v63
	v_cvt_pk_bf16_f32 v90, v64, v65
	v_cvt_pk_bf16_f32 v91, v66, v67
	global_store_dwordx4 v101, v[88:91], s[50:51]
	s_waitcnt lgkmcnt(4)
	v_pk_mul_f32 v[68:69], v[68:69], v[12:13]
	v_pk_mul_f32 v[70:71], v[70:71], v[14:15]
	v_pk_mul_f32 v[72:73], v[72:73], v[16:17]
	v_pk_mul_f32 v[74:75], v[74:75], v[18:19]
	v_cvt_pk_bf16_f32 v92, v68, v69
	v_cvt_pk_bf16_f32 v93, v70, v71
	v_cvt_pk_bf16_f32 v94, v72, v73
	v_cvt_pk_bf16_f32 v95, v74, v75
	global_store_dwordx4 v102, v[92:95], s[50:51]
	s_waitcnt lgkmcnt(0)
	v_pk_mul_f32 v[76:77], v[76:77], v[12:13]
	v_pk_mul_f32 v[78:79], v[78:79], v[14:15]
	v_pk_mul_f32 v[80:81], v[80:81], v[16:17]
	v_pk_mul_f32 v[82:83], v[82:83], v[18:19]
	v_cvt_pk_bf16_f32 v96, v76, v77
	v_cvt_pk_bf16_f32 v97, v78, v79
	v_cvt_pk_bf16_f32 v98, v80, v81
	v_cvt_pk_bf16_f32 v99, v82, v83
	global_store_dwordx4 v103, v[96:99], s[50:51]
	s_mov_b32 s50, s70
	s_mov_b32 s51, s71
	s_mov_b32 s52, s72
	s_mov_b32 s53, s73
	s_mov_b32 s54, s74
	s_mov_b32 s55, s75
	s_mov_b32 s56, s76
	s_mov_b32 s57, s77
	s_mov_b32 s58, s59
	s_cmp_eq_u32 s63, 1
	s_cbranch_scc1 .Lq0_loop
	s_waitcnt vmcnt(0)
	v_readlane_b32 s6, v250, 0
	v_readlane_b32 s7, v250, 1
	v_readlane_b32 s8, v250, 2
	v_readlane_b32 s9, v250, 3
	v_readlane_b32 s10, v250, 4
	v_readlane_b32 s11, v250, 5
	v_readlane_b32 s12, v250, 6
	v_readlane_b32 s13, v250, 7
	v_readlane_b32 s14, v250, 8
	v_readlane_b32 s15, v250, 9
	v_readlane_b32 s16, v250, 10
	v_readlane_b32 s17, v250, 11
	v_readlane_b32 s18, v250, 12
	v_readlane_b32 s19, v250, 13
	v_readlane_b32 s20, v250, 14
	v_readlane_b32 s21, v250, 15
	v_readlane_b32 s22, v250, 16
	v_readlane_b32 s23, v250, 17
	v_readlane_b32 s24, v250, 18
	v_readlane_b32 s25, v250, 19
	v_readlane_b32 s26, v250, 20
	v_readlane_b32 s27, v250, 21
	v_readlane_b32 s28, v250, 22
	v_readlane_b32 s29, v250, 23
	v_readlane_b32 s30, v250, 24
	v_readlane_b32 s31, v250, 25
	v_readlane_b32 s32, v250, 26
	v_readlane_b32 s33, v250, 27
	v_readlane_b32 s34, v250, 28
	v_readlane_b32 s35, v250, 29
	v_readlane_b32 s36, v250, 30
	v_readlane_b32 s37, v250, 31
	v_readlane_b32 s38, v250, 32
	v_readlane_b32 s39, v250, 33
	v_readlane_b32 s40, v250, 34
	v_readlane_b32 s41, v250, 35
	v_readlane_b32 s42, v250, 36
	v_readlane_b32 s43, v250, 37
	v_readlane_b32 s44, v250, 38
	v_readlane_b32 s45, v250, 39
	v_readlane_b32 s46, v250, 40
	v_readlane_b32 s47, v250, 41
	v_readlane_b32 s48, v250, 42
	v_readlane_b32 s49, v250, 43
	v_readlane_b32 s50, v250, 44
	v_readlane_b32 s51, v250, 45
	v_readlane_b32 s52, v250, 46
	v_readlane_b32 s53, v250, 47
	v_readlane_b32 s54, v250, 48
	v_readlane_b32 s55, v250, 49
	v_readlane_b32 s56, v250, 50
	v_readlane_b32 s57, v250, 51
	v_readlane_b32 s58, v250, 52
	v_readlane_b32 s59, v250, 53
	v_readlane_b32 s60, v250, 54
	v_readlane_b32 s61, v250, 55
	v_readlane_b32 s62, v250, 56
	v_readlane_b32 s63, v250, 57
	v_readlane_b32 s64, v250, 58
	v_readlane_b32 s65, v250, 59
	v_readlane_b32 s66, v250, 60
	v_readlane_b32 s67, v250, 61
	v_readlane_b32 s68, v250, 62
	v_readlane_b32 s69, v250, 63
	v_readlane_b32 s70, v251, 0
	v_readlane_b32 s71, v251, 1
	v_readlane_b32 s72, v251, 2
	v_readlane_b32 s73, v251, 3
	v_readlane_b32 s74, v251, 4
	v_readlane_b32 s75, v251, 5
	v_readlane_b32 s76, v251, 6
	v_readlane_b32 s77, v251, 7
	v_readlane_b32 s78, v251, 8
	v_readlane_b32 s79, v251, 9
